# attention: static s_setprio 1 for waves 4-7 + loop bookkeeping hoisted above the step barriers (on top of saddr DMA)
# baseline (speedup 1.0000x reference)
; __global__ void __launch_bounds__(512, 2) fwd_kernel(Args args) {
;     ...
;         const float s1 = wave_sum(lam_q1[lane] * lam_k1[lane]), s2 = wave_sum(lam_q2[lane] * lam_k2[lane]);
;         const float lam = __expf(s1) - __expf(s2) + LAMBDA_INIT;
;         for (int i = 0; ; ++i) { const int L = i * G + vcu, NU = NBATCH * NH * (SEQ / 256); if (L >= NU) break;
;             const int bh = L >> 3, qb = L & 7, Ln = L + G, nbh = Ln >> 3;
;             att::attn_unit(bh >> 3, bh & 7, qb, i == 0, Ln < NU, nbh >> 3, nbh & 7, QO, KB, VB, lam, (char*)lds_raw); }
.LBB0_367:
	s_or_b64 exec, exec, s[0:1]
	v_lshlrev_b32_e32 v1, 2, v162
	s_barrier
	global_load_dword v2, v1, s[48:49]
	global_load_dword v3, v1, s[50:51]
	global_load_dword v4, v1, s[16:17]
	global_load_dword v5, v1, s[18:19]
	v_mbcnt_lo_u32_b32 v1, -1, 0
	v_mbcnt_hi_u32_b32 v6, -1, v1
	v_and_b32_e32 v1, 64, v6
	v_xor_b32_e32 v7, 1, v6
	v_add_u32_e32 v13, 64, v1
	v_cmp_lt_i32_e32 vcc, v7, v13
	v_xor_b32_e32 v8, 2, v6
	v_xor_b32_e32 v9, 4, v6
	v_cndmask_b32_e32 v1, v6, v7, vcc
	v_lshlrev_b32_e32 v1, 2, v1
	v_cmp_lt_i32_e32 vcc, v8, v13
	v_xor_b32_e32 v10, 8, v6
	v_xor_b32_e32 v11, 16, v6
	v_cndmask_b32_e32 v8, v6, v8, vcc
	v_lshlrev_b32_e32 v234, 2, v8
	v_cmp_lt_i32_e32 vcc, v9, v13
	v_xor_b32_e32 v12, 32, v6
	s_cmpk_gt_i32 s86, 0x5ff
	s_mov_b32 s1, 0
	s_waitcnt vmcnt(2)
	v_mul_f32_e32 v7, v2, v3
	ds_bpermute_b32 v7, v1, v7
	s_waitcnt vmcnt(0)
	v_mul_f32_e32 v14, v4, v5
	ds_bpermute_b32 v14, v1, v14
	s_waitcnt lgkmcnt(1)
	v_fmac_f32_e32 v7, v2, v3
	ds_bpermute_b32 v2, v234, v7
	s_waitcnt lgkmcnt(1)
	v_fmac_f32_e32 v14, v4, v5
	ds_bpermute_b32 v3, v234, v14
	v_cndmask_b32_e32 v4, v6, v9, vcc
	v_lshlrev_b32_e32 v235, 2, v4
	s_waitcnt lgkmcnt(1)
	v_add_f32_e32 v2, v7, v2
	ds_bpermute_b32 v4, v235, v2
	s_waitcnt lgkmcnt(1)
	v_add_f32_e32 v3, v14, v3
	ds_bpermute_b32 v5, v235, v3
	v_cmp_lt_i32_e32 vcc, v10, v13
	s_waitcnt lgkmcnt(1)
	v_add_f32_e32 v2, v2, v4
	v_cndmask_b32_e32 v7, v6, v10, vcc
	v_lshlrev_b32_e32 v236, 2, v7
	s_waitcnt lgkmcnt(0)
	v_add_f32_e32 v3, v3, v5
	ds_bpermute_b32 v4, v236, v2
	ds_bpermute_b32 v5, v236, v3
	v_cmp_lt_i32_e32 vcc, v11, v13
	s_waitcnt lgkmcnt(1)
	v_add_f32_e32 v2, v2, v4
	v_cndmask_b32_e32 v7, v6, v11, vcc
	v_lshlrev_b32_e32 v237, 2, v7
	s_waitcnt lgkmcnt(0)
	v_add_f32_e32 v3, v3, v5
	ds_bpermute_b32 v4, v237, v2
	ds_bpermute_b32 v5, v237, v3
	v_cmp_lt_i32_e32 vcc, v12, v13
	s_waitcnt lgkmcnt(1)
	v_add_f32_e32 v2, v2, v4
	v_cndmask_b32_e32 v6, v6, v12, vcc
	v_lshlrev_b32_e32 v6, 2, v6
	s_waitcnt lgkmcnt(0)
	v_add_f32_e32 v3, v3, v5
	ds_bpermute_b32 v4, v6, v2
	ds_bpermute_b32 v5, v6, v3
	s_cbranch_scc1 .LBB0_385
	s_waitcnt lgkmcnt(1)
	v_add_f32_e32 v2, v2, v4
	s_waitcnt lgkmcnt(0)
	v_add_f32_e32 v3, v3, v5
	v_mul_f32_e32 v2, 0x3fb8aa3b, v2
	v_mul_f32_e32 v3, 0x3fb8aa3b, v3
	v_exp_f32_e32 v2, v2
	v_exp_f32_e32 v3, v3
	s_add_u32 s56, s62, 0xd220000
	s_addc_u32 s57, s63, 0
	s_lshl_b32 s72, s86, 8
	s_lshl_b32 s73, s15, 8
	v_writelane_b32 v248, s78, 4
	v_sub_f32_e32 v2, v2, v3
	s_add_u32 s76, s62, 0x13220000
	s_mov_b32 s65, s80
	v_writelane_b32 v248, s79, 5
	v_add_f32_e32 v238, 0x3e4ccccd, v2
	s_addc_u32 s77, s63, 0
	s_movk_i32 s78, 0x1e0
	s_mov_b64 s[2:3], 0x800
	s_mov_b64 s[4:5], 0x20000
	s_mov_b64 s[8:9], 0x20800
	s_mov_b64 s[10:11], 0x3c0000
	s_mov_b64 s[16:17], 0x3c0800
	s_mov_b64 s[18:19], 0x3e0000
	s_mov_b64 s[20:21], 0x3e0800
	v_mov_b32_e32 v203, 0
	s_mov_b64 s[22:23], 0x40000
	s_mov_b64 s[24:25], 0x60000
	s_mov_b64 s[30:31], 0x80000
	s_mov_b64 s[44:45], 0x40800
	v_mov_b32_e32 v239, 0x358637bd
	s_movk_i32 s79, 0xffe0
	s_mov_b32 s0, s86
	s_mov_b32 s80, 0
	v_readfirstlane_b32 s98, v0
	s_lshr_b32 s98, s98, 6
	s_cmp_ge_u32 s98, 4
	s_cbranch_scc0 .Latt_noprio
	s_setprio 1
.Latt_noprio:
	s_branch .LBB0_370

; #define ATT_WAIT_BAR(N) asm volatile("s_waitcnt vmcnt(" #N ") lgkmcnt(0)\n\ts_barrier" ::: "memory")
; #define ROT() do { sl_prev = sl_cur; sl_cur = sl_next; sl_next = (sl_next == 2) ? 0 : sl_next + 1; } while (0)
; __device__ __forceinline__ void attn_unit(int b, int h, int qb, bool first, bool has_next, int nb, int nh, bf16_t* QO, const bf16_t* __restrict__ K, const bf16_t* __restrict__ V, float lam, char* shm) {
;     ...
;         int t = 1;
; #pragma unroll 1
;         for (; t + 1 <= NT - 4; t += 2) {
;             STEP(pB0, pB1, pA0, pA1, t, true, true, true);     ATT_WAIT_BAR(3); ROT();
.LBB0_375:
	v_lshl_add_u32 v154, s60, 14, v241
	ds_read_b64_tr_b16 v[150:151], v154 offset:24576
	ds_read_b64_tr_b16 v[152:153], v154 offset:25088
	v_add_f32_e32 v106, v82, v83
	v_add_f32_e32 v106, v84, v106
	v_add_f32_e32 v106, v85, v106
	v_add_f32_e32 v106, v86, v106
	v_add_f32_e32 v106, v87, v106
	v_cvt_pk_bf16_f32 v174, v82, v83
	v_cvt_pk_bf16_f32 v175, v84, v85
	s_waitcnt lgkmcnt(9)
	v_mfma_f32_32x32x16_bf16 v[114:129], v[102:105], v[190:193], 0
	ds_read_b64_tr_b16 v[82:83], v154 offset:28672
	ds_read_b64_tr_b16 v[84:85], v154 offset:29184
	v_add_f32_e32 v102, v88, v106
	v_add_f32_e32 v102, v89, v102
	v_add_f32_e32 v102, v90, v102
	v_add_f32_e32 v155, v91, v102
	s_waitcnt lgkmcnt(10)
	v_mfma_f32_32x32x16_bf16 v[98:113], v[98:101], v[190:193], 0
	v_cvt_pk_bf16_f32 v176, v86, v87
	v_cvt_pk_bf16_f32 v177, v88, v89
	ds_read_b64_tr_b16 v[86:87], v154 offset:32768
	ds_read_b64_tr_b16 v[88:89], v154 offset:33280
	v_add_f32_e32 v155, v92, v155
	v_add_f32_e32 v155, v93, v155
	v_add_f32_e32 v155, v94, v155
	v_add_f32_e32 v155, v95, v155
	v_cvt_pk_bf16_f32 v170, v90, v91
	v_cvt_pk_bf16_f32 v171, v92, v93
	s_waitcnt lgkmcnt(11)
	v_mfma_f32_32x32x16_bf16 v[114:129], v[198:201], v[186:189], v[114:129]
	ds_read_b64_tr_b16 v[90:91], v154 offset:36864
	ds_read_b64_tr_b16 v[92:93], v154 offset:37376
	s_waitcnt lgkmcnt(12)
	v_mfma_f32_32x32x16_bf16 v[98:113], v[142:145], v[186:189], v[98:113]
	v_add_f32_e32 v155, v96, v155
	v_add_f32_e32 v155, v97, v155
	v_add_f32_e32 v155, v66, v155
	v_add_f32_e32 v155, v67, v155
	v_cvt_pk_bf16_f32 v172, v94, v95
	v_cvt_pk_bf16_f32 v173, v96, v97
	s_nop 0
	v_add_f32_e32 v94, v68, v155
	v_add_f32_e32 v94, v69, v94
	v_add_f32_e32 v94, v70, v94
	v_add_f32_e32 v94, v71, v94
	v_cvt_pk_bf16_f32 v166, v66, v67
	v_cvt_pk_bf16_f32 v167, v68, v69
	s_waitcnt lgkmcnt(11)
	v_mfma_f32_32x32x16_bf16 v[114:129], v[194:197], v[182:185], v[114:129]
	s_waitcnt lgkmcnt(10)
	v_mfma_f32_32x32x16_bf16 v[98:113], v[134:137], v[182:185], v[98:113]
	v_add_f32_e32 v66, v72, v94
	v_add_f32_e32 v66, v73, v66
	v_add_f32_e32 v66, v74, v66
	v_add_f32_e32 v66, v75, v66
	v_cvt_pk_bf16_f32 v168, v70, v71
	v_cvt_pk_bf16_f32 v169, v72, v73
	s_nop 0
	v_add_f32_e32 v66, v76, v66
	v_add_f32_e32 v66, v77, v66
	v_add_f32_e32 v66, v78, v66
	v_add_f32_e32 v66, v79, v66
	v_cvt_pk_bf16_f32 v162, v74, v75
	v_cvt_pk_bf16_f32 v163, v76, v77
	s_waitcnt lgkmcnt(9)
	v_mfma_f32_32x32x16_bf16 v[114:129], v[138:141], v[178:181], v[114:129]
	s_waitcnt lgkmcnt(8)
	v_mfma_f32_32x32x16_bf16 v[98:113], v[130:133], v[178:181], v[98:113]
	v_add_f32_e32 v66, v80, v66
	v_add_f32_e32 v66, v81, v66
	v_add_f32_e32 v66, 0, v66
	v_cvt_pk_bf16_f32 v164, v78, v79
	v_cvt_pk_bf16_f32 v165, v80, v81
	s_lshl_b32 s12, s7, 13
	s_add_i32 s12, s12, s91
	v_add_f32_e32 v198, v202, v66
	v_lshl_add_u64 v[66:67], v[146:147], 0, s[24:25]
	s_mov_b32 s13, m0
	s_mov_b32 m0, s12
	s_nop 0
	global_load_lds_dwordx4 v[66:67], off
	s_mov_b32 m0, s13
	s_lshl_b32 s12, s0, 14
	v_lshl_add_u64 v[66:67], v[148:149], 0, s[4:5]
	s_add_i32 s12, s12, s92
	s_mov_b32 s13, m0
	s_mov_b32 m0, s12
	s_nop 0
	global_load_lds_dwordx4 v[66:67], off
	s_mov_b32 m0, s13
	v_lshl_add_u64 v[66:67], v[148:149], 0, s[8:9]
	s_addk_i32 s12, 0x2000
	s_mov_b32 s13, m0
	s_mov_b32 m0, s12
	s_nop 0
	global_load_lds_dwordx4 v[66:67], off
	s_mov_b32 m0, s13
	s_waitcnt lgkmcnt(6)
	v_mfma_f32_32x32x16_bf16 v[50:65], v[174:177], v[150:153], v[50:65]
	v_exp_f32_e32 v114, v114
	v_exp_f32_e32 v115, v115
	ds_read_b64_tr_b16 v[66:67], v154 offset:25600
	ds_read_b64_tr_b16 v[68:69], v154 offset:26112
	s_waitcnt lgkmcnt(6)
	v_mfma_f32_32x32x16_bf16 v[34:49], v[174:177], v[82:85], v[34:49]
	v_exp_f32_e32 v116, v116
	v_exp_f32_e32 v117, v117
	ds_read_b64_tr_b16 v[70:71], v154 offset:29696
	ds_read_b64_tr_b16 v[72:73], v154 offset:30208
	s_waitcnt lgkmcnt(6)
	v_mfma_f32_32x32x16_bf16 v[18:33], v[174:177], v[86:89], v[18:33]
	v_exp_f32_e32 v118, v118
	v_exp_f32_e32 v119, v119
	ds_read_b64_tr_b16 v[74:75], v154 offset:33792
	ds_read_b64_tr_b16 v[76:77], v154 offset:34304
	s_waitcnt lgkmcnt(6)
	v_mfma_f32_32x32x16_bf16 v[2:17], v[174:177], v[90:93], v[2:17]
	v_exp_f32_e32 v120, v120
	v_exp_f32_e32 v121, v121
	ds_read_b64_tr_b16 v[78:79], v154 offset:37888
	ds_read_b64_tr_b16 v[80:81], v154 offset:38400
	s_waitcnt lgkmcnt(6)
	v_mfma_f32_32x32x16_bf16 v[50:65], v[170:173], v[66:69], v[50:65]
	v_exp_f32_e32 v122, v122
	v_exp_f32_e32 v123, v123
	ds_read_b64_tr_b16 v[82:83], v154 offset:26624
	ds_read_b64_tr_b16 v[84:85], v154 offset:27136
	s_waitcnt lgkmcnt(6)
	v_mfma_f32_32x32x16_bf16 v[34:49], v[170:173], v[70:73], v[34:49]
	v_exp_f32_e32 v124, v124
	v_exp_f32_e32 v125, v125
	ds_read_b64_tr_b16 v[66:67], v154 offset:30720
	ds_read_b64_tr_b16 v[68:69], v154 offset:31232
	s_waitcnt lgkmcnt(6)
	v_mfma_f32_32x32x16_bf16 v[18:33], v[170:173], v[74:77], v[18:33]
	s_lshl_b32 s60, s0, 13
	v_exp_f32_e32 v126, v126
	v_exp_f32_e32 v127, v127
	v_add_u32_e32 v90, s60, v243
	ds_read_b128 v[70:73], v90
	ds_read_b128 v[130:133], v90 offset:512
	ds_read_b64_tr_b16 v[86:87], v154 offset:34816
	ds_read_b64_tr_b16 v[88:89], v154 offset:35328
	s_waitcnt lgkmcnt(8)
	v_mfma_f32_32x32x16_bf16 v[2:17], v[170:173], v[78:81], v[2:17]
	v_exp_f32_e32 v128, v128
	v_exp_f32_e32 v129, v129
	ds_read_b64_tr_b16 v[74:75], v154 offset:38912
	ds_read_b64_tr_b16 v[76:77], v154 offset:39424
	s_waitcnt lgkmcnt(8)
	v_mfma_f32_32x32x16_bf16 v[50:65], v[166:169], v[82:85], v[50:65]
	v_exp_f32_e32 v98, v98
	v_exp_f32_e32 v99, v99
	ds_read_b128 v[134:137], v90 offset:2048
	ds_read_b128 v[138:141], v90 offset:2560
	ds_read_b64_tr_b16 v[78:79], v154 offset:27648
	ds_read_b64_tr_b16 v[80:81], v154 offset:28160
	s_waitcnt lgkmcnt(10)
; #define ATT_WAIT_BAR(N) asm volatile("s_waitcnt vmcnt(" #N ") lgkmcnt(0)\n\ts_barrier" ::: "memory")
; #define ROT() do { sl_prev = sl_cur; sl_cur = sl_next; sl_next = (sl_next == 2) ? 0 : sl_next + 1; } while (0)
; __device__ __forceinline__ void attn_unit(int b, int h, int qb, bool first, bool has_next, int nb, int nh, bf16_t* QO, const bf16_t* __restrict__ K, const bf16_t* __restrict__ V, float lam, char* shm) {
;     ...
;         int t = 1;
; #pragma unroll 1
;         for (; t + 1 <= NT - 4; t += 2) {
;             STEP(pB0, pB1, pA0, pA1, t, true, true, true);     ATT_WAIT_BAR(3); ROT();
;             STEP(pA0, pA1, pB0, pB1, t + 1, true, true, true); ATT_WAIT_BAR(3); ROT();
	v_mfma_f32_32x32x16_bf16 v[34:49], v[166:169], v[66:69], v[34:49]
	v_exp_f32_e32 v100, v100
	v_exp_f32_e32 v101, v101
	ds_read_b64_tr_b16 v[82:83], v154 offset:31744
	ds_read_b64_tr_b16 v[84:85], v154 offset:32256
	s_waitcnt lgkmcnt(8)
	v_mfma_f32_32x32x16_bf16 v[18:33], v[166:169], v[86:89], v[18:33]
	v_exp_f32_e32 v102, v102
	v_exp_f32_e32 v103, v103
	ds_read_b128 v[142:145], v90 offset:4096
	ds_read_b128 v[150:153], v90 offset:4608
	ds_read_b64_tr_b16 v[66:67], v154 offset:35840
	ds_read_b64_tr_b16 v[68:69], v154 offset:36352
	s_waitcnt lgkmcnt(10)
	v_mfma_f32_32x32x16_bf16 v[2:17], v[166:169], v[74:77], v[2:17]
	v_exp_f32_e32 v104, v104
	v_exp_f32_e32 v105, v105
	ds_read_b64_tr_b16 v[86:87], v154 offset:39936
	ds_read_b64_tr_b16 v[88:89], v154 offset:40448
	s_waitcnt lgkmcnt(8)
	v_mfma_f32_32x32x16_bf16 v[50:65], v[162:165], v[78:81], v[50:65]
	ds_read_b128 v[154:157], v90 offset:6144
	ds_read_b128 v[158:161], v90 offset:6656
	v_exp_f32_e32 v106, v106
	v_exp_f32_e32 v107, v107
	s_waitcnt lgkmcnt(8)
	v_mfma_f32_32x32x16_bf16 v[34:49], v[162:165], v[82:85], v[34:49]
	v_exp_f32_e32 v108, v108
	v_exp_f32_e32 v109, v109
	s_waitcnt lgkmcnt(4)
	v_mfma_f32_32x32x16_bf16 v[18:33], v[162:165], v[66:69], v[18:33]
	v_exp_f32_e32 v110, v110
	v_exp_f32_e32 v111, v111
	s_waitcnt lgkmcnt(2)
	v_mfma_f32_32x32x16_bf16 v[2:17], v[162:165], v[86:89], v[2:17]
	v_exp_f32_e32 v112, v112
	v_exp_f32_e32 v113, v113
	s_waitcnt vmcnt(3) lgkmcnt(0)
	s_add_i32 s12, s0, 1
	s_cmp_lg_u32 s0, 2
	s_cselect_b32 s33, s12, 0
	s_barrier
	v_lshl_add_u32 v244, s7, 14, v241
	ds_read_b64_tr_b16 v[194:195], v244 offset:24576
	ds_read_b64_tr_b16 v[196:197], v244 offset:25088
	v_mfma_f32_32x32x16_bf16 v[82:97], v[70:73], v[190:193], 0
	v_add_f32_e32 v66, v114, v115
	v_add_f32_e32 v66, v116, v66
	v_add_f32_e32 v66, v117, v66
	v_add_f32_e32 v66, v118, v66
	v_add_f32_e32 v66, v119, v66
	v_cvt_pk_bf16_f32 v174, v114, v115
	v_cvt_pk_bf16_f32 v175, v116, v117
	ds_read_b64_tr_b16 v[114:115], v244 offset:28672
	ds_read_b64_tr_b16 v[116:117], v244 offset:29184
	v_add_f32_e32 v66, v120, v66
	v_add_f32_e32 v66, v121, v66
	v_add_f32_e32 v66, v122, v66
	v_add_f32_e32 v162, v123, v66
	v_mfma_f32_32x32x16_bf16 v[66:81], v[130:133], v[190:193], 0
	v_cvt_pk_bf16_f32 v176, v118, v119
	v_cvt_pk_bf16_f32 v177, v120, v121
	ds_read_b64_tr_b16 v[118:119], v244 offset:32768
	ds_read_b64_tr_b16 v[120:121], v244 offset:33280
	v_mfma_f32_32x32x16_bf16 v[82:97], v[134:137], v[186:189], v[82:97]
	v_add_f32_e32 v130, v124, v162
	v_add_f32_e32 v130, v125, v130
	v_add_f32_e32 v130, v126, v130
	v_add_f32_e32 v130, v127, v130
	v_cvt_pk_bf16_f32 v170, v122, v123
	v_cvt_pk_bf16_f32 v171, v124, v125
	ds_read_b64_tr_b16 v[122:123], v244 offset:36864
	ds_read_b64_tr_b16 v[124:125], v244 offset:37376
	v_mfma_f32_32x32x16_bf16 v[66:81], v[138:141], v[186:189], v[66:81]
	v_add_f32_e32 v130, v128, v130
	v_add_f32_e32 v130, v129, v130
	v_add_f32_e32 v130, v98, v130
	v_add_f32_e32 v130, v99, v130
	v_cvt_pk_bf16_f32 v172, v126, v127
	v_cvt_pk_bf16_f32 v173, v128, v129
	v_mfma_f32_32x32x16_bf16 v[82:97], v[142:145], v[182:185], v[82:97]
	v_add_f32_e32 v126, v100, v130
	v_add_f32_e32 v126, v101, v126
	v_add_f32_e32 v126, v102, v126
	v_add_f32_e32 v126, v103, v126
	v_cvt_pk_bf16_f32 v166, v98, v99
	v_cvt_pk_bf16_f32 v167, v100, v101
	v_mfma_f32_32x32x16_bf16 v[66:81], v[150:153], v[182:185], v[66:81]
	v_add_f32_e32 v98, v104, v126
	v_add_f32_e32 v98, v105, v98
	v_add_f32_e32 v98, v106, v98
	v_add_f32_e32 v98, v107, v98
	v_cvt_pk_bf16_f32 v168, v102, v103
	v_cvt_pk_bf16_f32 v169, v104, v105
	s_waitcnt lgkmcnt(9)
	v_mfma_f32_32x32x16_bf16 v[82:97], v[154:157], v[178:181], v[82:97]
	v_add_f32_e32 v98, v108, v98
	v_add_f32_e32 v98, v109, v98
	v_add_f32_e32 v98, v110, v98
	v_add_f32_e32 v98, v111, v98
	v_cvt_pk_bf16_f32 v162, v106, v107
	v_cvt_pk_bf16_f32 v163, v108, v109
	s_waitcnt lgkmcnt(8)
	v_mfma_f32_32x32x16_bf16 v[66:81], v[158:161], v[178:181], v[66:81]
	v_add_f32_e32 v98, v112, v98
	v_add_f32_e32 v98, v113, v98
	v_add_f32_e32 v98, 0, v98
	v_cvt_pk_bf16_f32 v164, v110, v111
	v_cvt_pk_bf16_f32 v165, v112, v113
	s_add_i32 s7, s60, s91
	v_add_f32_e32 v202, v198, v98
	v_lshl_add_u64 v[98:99], v[146:147], 0, s[30:31]
	s_mov_b32 s12, m0
	s_mov_b32 m0, s7
	s_nop 0
	global_load_lds_dwordx4 v[98:99], off
	s_mov_b32 m0, s12
	s_lshl_b32 s7, s33, 14
	v_lshl_add_u64 v[106:107], v[148:149], 0, s[22:23]
	s_add_i32 s7, s7, s92
	s_mov_b32 s12, m0
	s_mov_b32 m0, s7
	s_nop 0
	global_load_lds_dwordx4 v[106:107], off
	s_mov_b32 m0, s12
	v_lshl_add_u64 v[98:99], v[148:149], 0, s[44:45]
	s_addk_i32 s7, 0x2000
	s_mov_b32 s12, m0
	s_mov_b32 m0, s7
	s_nop 0
	global_load_lds_dwordx4 v[98:99], off
	s_mov_b32 m0, s12
	s_waitcnt lgkmcnt(6)
	v_mfma_f32_32x32x16_bf16 v[50:65], v[174:177], v[194:197], v[50:65]
	v_exp_f32_e32 v82, v82
	v_exp_f32_e32 v83, v83
	ds_read_b64_tr_b16 v[98:99], v244 offset:25600
	ds_read_b64_tr_b16 v[100:101], v244 offset:26112
	s_waitcnt lgkmcnt(6)
	v_mfma_f32_32x32x16_bf16 v[34:49], v[174:177], v[114:117], v[34:49]
	v_exp_f32_e32 v84, v84
	v_exp_f32_e32 v85, v85
	ds_read_b64_tr_b16 v[102:103], v244 offset:29696
	ds_read_b64_tr_b16 v[104:105], v244 offset:30208
	s_waitcnt lgkmcnt(6)
	v_mfma_f32_32x32x16_bf16 v[18:33], v[174:177], v[118:121], v[18:33]
	v_exp_f32_e32 v86, v86
	v_exp_f32_e32 v87, v87
	ds_read_b64_tr_b16 v[108:109], v244 offset:33792
	ds_read_b64_tr_b16 v[110:111], v244 offset:34304
	s_waitcnt lgkmcnt(6)
	v_mfma_f32_32x32x16_bf16 v[2:17], v[174:177], v[122:125], v[2:17]
	v_exp_f32_e32 v88, v88
	v_exp_f32_e32 v89, v89
	ds_read_b64_tr_b16 v[112:113], v244 offset:37888
	ds_read_b64_tr_b16 v[114:115], v244 offset:38400
	s_waitcnt lgkmcnt(6)
; #define ATT_WAIT_BAR(N) asm volatile("s_waitcnt vmcnt(" #N ") lgkmcnt(0)\n\ts_barrier" ::: "memory")
; #define ROT() do { sl_prev = sl_cur; sl_cur = sl_next; sl_next = (sl_next == 2) ? 0 : sl_next + 1; } while (0)
; __device__ __forceinline__ void attn_unit(int b, int h, int qb, bool first, bool has_next, int nb, int nh, bf16_t* QO, const bf16_t* __restrict__ K, const bf16_t* __restrict__ V, float lam, char* shm) {
;     ...
;         for (; t + 1 <= NT - 4; t += 2) {
;             STEP(pB0, pB1, pA0, pA1, t, true, true, true);     ATT_WAIT_BAR(3); ROT();
;             STEP(pA0, pA1, pB0, pB1, t + 1, true, true, true); ATT_WAIT_BAR(3); ROT();
;         }
;         STEP(pB0, pB1, pA0, pA1, NT - 3, false, true, true);   ATT_WAIT_BAR(2); ROT();
	v_mfma_f32_32x32x16_bf16 v[50:65], v[170:173], v[98:101], v[50:65]
	v_exp_f32_e32 v90, v90
	v_exp_f32_e32 v91, v91
	ds_read_b64_tr_b16 v[116:117], v244 offset:26624
	ds_read_b64_tr_b16 v[118:119], v244 offset:27136
	s_waitcnt lgkmcnt(6)
	v_mfma_f32_32x32x16_bf16 v[34:49], v[170:173], v[102:105], v[34:49]
	v_exp_f32_e32 v92, v92
	v_exp_f32_e32 v93, v93
	ds_read_b64_tr_b16 v[120:121], v244 offset:30720
	ds_read_b64_tr_b16 v[122:123], v244 offset:31232
	s_waitcnt lgkmcnt(6)
	v_mfma_f32_32x32x16_bf16 v[18:33], v[170:173], v[108:111], v[18:33]
	v_exp_f32_e32 v94, v94
	v_exp_f32_e32 v95, v95
	v_lshl_add_u32 v128, s33, 13, v243
	ds_read_b128 v[102:105], v128
	ds_read_b128 v[98:101], v128 offset:512
	ds_read_b64_tr_b16 v[124:125], v244 offset:34816
	ds_read_b64_tr_b16 v[126:127], v244 offset:35328
	s_waitcnt lgkmcnt(8)
	v_mfma_f32_32x32x16_bf16 v[2:17], v[170:173], v[112:115], v[2:17]
	v_exp_f32_e32 v96, v96
	v_exp_f32_e32 v97, v97
	ds_read_b64_tr_b16 v[108:109], v244 offset:38912
	ds_read_b64_tr_b16 v[110:111], v244 offset:39424
	s_waitcnt lgkmcnt(8)
	v_mfma_f32_32x32x16_bf16 v[50:65], v[166:169], v[116:119], v[50:65]
	v_exp_f32_e32 v66, v66
	v_exp_f32_e32 v67, v67
	ds_read_b128 v[198:201], v128 offset:2048
	ds_read_b128 v[142:145], v128 offset:2560
	ds_read_b64_tr_b16 v[112:113], v244 offset:27648
	ds_read_b64_tr_b16 v[114:115], v244 offset:28160
	s_waitcnt lgkmcnt(10)
	v_mfma_f32_32x32x16_bf16 v[34:49], v[166:169], v[120:123], v[34:49]
	v_exp_f32_e32 v68, v68
	v_exp_f32_e32 v69, v69
	ds_read_b64_tr_b16 v[116:117], v244 offset:31744
	ds_read_b64_tr_b16 v[118:119], v244 offset:32256
	s_waitcnt lgkmcnt(8)
	v_mfma_f32_32x32x16_bf16 v[18:33], v[166:169], v[124:127], v[18:33]
	v_exp_f32_e32 v70, v70
	v_exp_f32_e32 v71, v71
	ds_read_b128 v[194:197], v128 offset:4096
	ds_read_b128 v[134:137], v128 offset:4608
	ds_read_b64_tr_b16 v[120:121], v244 offset:35840
	ds_read_b64_tr_b16 v[122:123], v244 offset:36352
	s_waitcnt lgkmcnt(10)
	v_mfma_f32_32x32x16_bf16 v[2:17], v[166:169], v[108:111], v[2:17]
	v_exp_f32_e32 v72, v72
	v_exp_f32_e32 v73, v73
	ds_read_b64_tr_b16 v[124:125], v244 offset:39936
	ds_read_b64_tr_b16 v[126:127], v244 offset:40448
	s_waitcnt lgkmcnt(8)
	v_mfma_f32_32x32x16_bf16 v[50:65], v[162:165], v[112:115], v[50:65]
	ds_read_b128 v[138:141], v128 offset:6144
	ds_read_b128 v[130:133], v128 offset:6656
	v_exp_f32_e32 v74, v74
	v_exp_f32_e32 v75, v75
	s_waitcnt lgkmcnt(8)
	v_mfma_f32_32x32x16_bf16 v[34:49], v[162:165], v[116:119], v[34:49]
	v_exp_f32_e32 v76, v76
	v_exp_f32_e32 v77, v77
	s_waitcnt lgkmcnt(4)
	v_mfma_f32_32x32x16_bf16 v[18:33], v[162:165], v[120:123], v[18:33]
	v_exp_f32_e32 v78, v78
	v_exp_f32_e32 v79, v79
	s_waitcnt lgkmcnt(2)
	v_mfma_f32_32x32x16_bf16 v[2:17], v[162:165], v[124:127], v[2:17]
	v_exp_f32_e32 v80, v80
	v_exp_f32_e32 v81, v81
	s_add_i32 s12, s33, 1
	s_waitcnt vmcnt(3) lgkmcnt(0)
	s_cmp_lg_u32 s33, 2
	s_mov_b32 s60, s0
	s_cselect_b32 s0, s12, 0
	s_add_i32 s6, s6, 2
	v_lshl_add_u64 v[146:147], v[146:147], 0, s[22:23]
	v_mov_b64_e32 v[148:149], v[106:107]
	s_mov_b32 s7, s33
	s_cmp_lt_u32 s6, 26
	s_barrier
	s_cbranch_scc1 .LBB0_375
	ds_read_b64_tr_b16 v[106:107], v241 offset:40960
	ds_read_b64_tr_b16 v[108:109], v241 offset:41472
	v_add_f32_e32 v110, v82, v83
	v_add_f32_e32 v110, v84, v110
	v_add_f32_e32 v110, v85, v110
	v_add_f32_e32 v110, v86, v110
	v_add_f32_e32 v110, v87, v110
	v_cvt_pk_bf16_f32 v174, v82, v83
	v_cvt_pk_bf16_f32 v175, v84, v85
	v_mfma_f32_32x32x16_bf16 v[146:161], v[102:105], v[190:193], 0
	ds_read_b64_tr_b16 v[82:83], v241 offset:45056
	ds_read_b64_tr_b16 v[84:85], v241 offset:45568
	v_mfma_f32_32x32x16_bf16 v[114:129], v[98:101], v[190:193], 0
	v_add_f32_e32 v102, v88, v110
	v_add_f32_e32 v102, v89, v102
	v_add_f32_e32 v102, v90, v102
	v_add_f32_e32 v102, v91, v102
	v_cvt_pk_bf16_f32 v176, v86, v87
	v_cvt_pk_bf16_f32 v177, v88, v89
	ds_read_b64_tr_b16 v[86:87], v241 offset:49152
	ds_read_b64_tr_b16 v[88:89], v241 offset:49664
	v_add_f32_e32 v98, v92, v102
	v_add_f32_e32 v98, v93, v98
	v_add_f32_e32 v98, v94, v98
	v_add_f32_e32 v98, v95, v98
	v_cvt_pk_bf16_f32 v170, v90, v91
	v_cvt_pk_bf16_f32 v171, v92, v93
	v_mfma_f32_32x32x16_bf16 v[146:161], v[198:201], v[186:189], v[146:161]
	ds_read_b64_tr_b16 v[90:91], v241 offset:53248
	ds_read_b64_tr_b16 v[92:93], v241 offset:53760
	v_mfma_f32_32x32x16_bf16 v[114:129], v[142:145], v[186:189], v[114:129]
	v_add_f32_e32 v98, v96, v98
	v_add_f32_e32 v98, v97, v98
	v_add_f32_e32 v98, v66, v98
	v_add_f32_e32 v98, v67, v98
	v_cvt_pk_bf16_f32 v172, v94, v95
	v_cvt_pk_bf16_f32 v173, v96, v97
	s_nop 0
	v_add_f32_e32 v94, v68, v98
	v_add_f32_e32 v94, v69, v94
	v_add_f32_e32 v94, v70, v94
	v_add_f32_e32 v94, v71, v94
	v_cvt_pk_bf16_f32 v166, v66, v67
	v_cvt_pk_bf16_f32 v167, v68, v69
	v_mfma_f32_32x32x16_bf16 v[146:161], v[194:197], v[182:185], v[146:161]
	v_mfma_f32_32x32x16_bf16 v[114:129], v[134:137], v[182:185], v[114:129]
	v_add_f32_e32 v66, v72, v94
	v_add_f32_e32 v66, v73, v66
	v_add_f32_e32 v66, v74, v66
	v_add_f32_e32 v66, v75, v66
	v_cvt_pk_bf16_f32 v168, v70, v71
	v_cvt_pk_bf16_f32 v169, v72, v73
	s_nop 0
	v_add_f32_e32 v66, v76, v66
	v_add_f32_e32 v66, v77, v66
	v_add_f32_e32 v66, v78, v66
	v_add_f32_e32 v66, v79, v66
	v_cvt_pk_bf16_f32 v162, v74, v75
	v_cvt_pk_bf16_f32 v163, v76, v77
	s_waitcnt lgkmcnt(9)
	v_mfma_f32_32x32x16_bf16 v[146:161], v[138:141], v[178:181], v[146:161]
	s_waitcnt lgkmcnt(8)
	v_mfma_f32_32x32x16_bf16 v[114:129], v[130:133], v[178:181], v[114:129]
	v_add_f32_e32 v66, v80, v66
	v_add_f32_e32 v66, v81, v66
	v_add_f32_e32 v194, 0, v66
	v_cvt_pk_bf16_f32 v164, v78, v79
	v_cvt_pk_bf16_f32 v165, v80, v81
	s_mov_b32 s0, m0
	s_mov_b32 m0, s92
	s_nop 0
	global_load_lds_dwordx4 v[214:215], off
	s_mov_b32 m0, s0
	s_add_i32 s0, s92, 0x2000
	s_mov_b32 s6, m0
	s_mov_b32 m0, s0
	s_nop 0
	global_load_lds_dwordx4 v[216:217], off
	s_mov_b32 m0, s6
	s_waitcnt lgkmcnt(6)
; #define ATT_WAIT_BAR(N) asm volatile("s_waitcnt vmcnt(" #N ") lgkmcnt(0)\n\ts_barrier" ::: "memory")
; #define ROT() do { sl_prev = sl_cur; sl_cur = sl_next; sl_next = (sl_next == 2) ? 0 : sl_next + 1; } while (0)
; __device__ __forceinline__ void attn_unit(int b, int h, int qb, bool first, bool has_next, int nb, int nh, bf16_t* QO, const bf16_t* __restrict__ K, const bf16_t* __restrict__ V, float lam, char* shm) {
;     ...
;         STEP(pB0, pB1, pA0, pA1, NT - 3, false, true, true);   ATT_WAIT_BAR(2); ROT();
;         STEP(pA0, pA1, pB0, pB1, NT - 2, false, true, true);   ATT_WAIT_BAR(0); ROT();
	v_mfma_f32_32x32x16_bf16 v[50:65], v[174:177], v[106:109], v[50:65]
	s_nop 1
	v_exp_f32_e32 v146, v146
	v_exp_f32_e32 v147, v147
	ds_read_b64_tr_b16 v[66:67], v241 offset:41984
	ds_read_b64_tr_b16 v[68:69], v241 offset:42496
	s_waitcnt lgkmcnt(6)
	v_mfma_f32_32x32x16_bf16 v[34:49], v[174:177], v[82:85], v[34:49]
	v_exp_f32_e32 v148, v148
	v_exp_f32_e32 v149, v149
	ds_read_b64_tr_b16 v[70:71], v241 offset:46080
	ds_read_b64_tr_b16 v[72:73], v241 offset:46592
	s_waitcnt lgkmcnt(6)
	v_mfma_f32_32x32x16_bf16 v[18:33], v[174:177], v[86:89], v[18:33]
	v_exp_f32_e32 v150, v150
	v_exp_f32_e32 v151, v151
	ds_read_b64_tr_b16 v[74:75], v241 offset:50176
	ds_read_b64_tr_b16 v[76:77], v241 offset:50688
	s_waitcnt lgkmcnt(6)
	v_mfma_f32_32x32x16_bf16 v[2:17], v[174:177], v[90:93], v[2:17]
	v_exp_f32_e32 v152, v152
	v_exp_f32_e32 v153, v153
	ds_read_b64_tr_b16 v[78:79], v241 offset:54272
	ds_read_b64_tr_b16 v[80:81], v241 offset:54784
	s_waitcnt lgkmcnt(6)
	v_mfma_f32_32x32x16_bf16 v[50:65], v[170:173], v[66:69], v[50:65]
	v_exp_f32_e32 v154, v154
	v_exp_f32_e32 v155, v155
	ds_read_b64_tr_b16 v[82:83], v241 offset:43008
	ds_read_b64_tr_b16 v[84:85], v241 offset:43520
	s_waitcnt lgkmcnt(6)
	v_mfma_f32_32x32x16_bf16 v[34:49], v[170:173], v[70:73], v[34:49]
	v_exp_f32_e32 v156, v156
	v_exp_f32_e32 v157, v157
	ds_read_b64_tr_b16 v[66:67], v241 offset:47104
	ds_read_b64_tr_b16 v[68:69], v241 offset:47616
	s_waitcnt lgkmcnt(6)
	v_mfma_f32_32x32x16_bf16 v[18:33], v[170:173], v[74:77], v[18:33]
	v_exp_f32_e32 v158, v158
	v_exp_f32_e32 v159, v159
	ds_read_b128 v[70:73], v243
	ds_read_b128 v[86:89], v243 offset:512
	ds_read_b64_tr_b16 v[90:91], v241 offset:51200
	ds_read_b64_tr_b16 v[92:93], v241 offset:51712
	s_waitcnt lgkmcnt(8)
	v_mfma_f32_32x32x16_bf16 v[2:17], v[170:173], v[78:81], v[2:17]
	v_exp_f32_e32 v160, v160
	v_exp_f32_e32 v161, v161
	ds_read_b64_tr_b16 v[74:75], v241 offset:55296
	ds_read_b64_tr_b16 v[76:77], v241 offset:55808
	s_waitcnt lgkmcnt(8)
	v_mfma_f32_32x32x16_bf16 v[50:65], v[166:169], v[82:85], v[50:65]
	v_exp_f32_e32 v114, v114
	v_exp_f32_e32 v115, v115
	ds_read_b128 v[78:81], v243 offset:2048
	ds_read_b128 v[94:97], v243 offset:2560
	ds_read_b64_tr_b16 v[98:99], v241 offset:44032
	ds_read_b64_tr_b16 v[100:101], v241 offset:44544
	s_waitcnt lgkmcnt(10)
	v_mfma_f32_32x32x16_bf16 v[34:49], v[166:169], v[66:69], v[34:49]
	v_exp_f32_e32 v116, v116
	v_exp_f32_e32 v117, v117
	ds_read_b64_tr_b16 v[82:83], v241 offset:48128
	ds_read_b64_tr_b16 v[84:85], v241 offset:48640
	s_waitcnt lgkmcnt(8)
	v_mfma_f32_32x32x16_bf16 v[18:33], v[166:169], v[90:93], v[18:33]
	v_exp_f32_e32 v118, v118
	v_exp_f32_e32 v119, v119
	ds_read_b128 v[66:69], v243 offset:4096
	ds_read_b128 v[196:199], v243 offset:4608
	ds_read_b64_tr_b16 v[102:103], v241 offset:52224
	ds_read_b64_tr_b16 v[104:105], v241 offset:52736
	s_waitcnt lgkmcnt(10)
	v_mfma_f32_32x32x16_bf16 v[2:17], v[166:169], v[74:77], v[2:17]
	v_exp_f32_e32 v120, v120
	v_exp_f32_e32 v121, v121
	ds_read_b64_tr_b16 v[90:91], v241 offset:56320
	ds_read_b64_tr_b16 v[92:93], v241 offset:56832
	s_waitcnt lgkmcnt(8)
	v_mfma_f32_32x32x16_bf16 v[50:65], v[162:165], v[98:101], v[50:65]
	ds_read_b128 v[74:77], v243 offset:6144
	ds_read_b128 v[244:247], v243 offset:6656
	v_exp_f32_e32 v122, v122
	v_exp_f32_e32 v123, v123
	s_waitcnt lgkmcnt(8)
	v_mfma_f32_32x32x16_bf16 v[34:49], v[162:165], v[82:85], v[34:49]
	v_exp_f32_e32 v124, v124
	v_exp_f32_e32 v125, v125
	s_waitcnt lgkmcnt(4)
	v_mfma_f32_32x32x16_bf16 v[18:33], v[162:165], v[102:105], v[18:33]
	v_exp_f32_e32 v126, v126
	v_exp_f32_e32 v127, v127
	s_waitcnt lgkmcnt(2)
	v_mfma_f32_32x32x16_bf16 v[2:17], v[162:165], v[90:93], v[2:17]
	v_exp_f32_e32 v128, v128
	v_exp_f32_e32 v129, v129
	s_waitcnt vmcnt(2) lgkmcnt(0)
	s_barrier
	ds_read_b64_tr_b16 v[82:83], v241 offset:57344
	ds_read_b64_tr_b16 v[84:85], v241 offset:57856
	v_add_f32_e32 v90, v146, v147
	v_add_f32_e32 v90, v148, v90
	v_add_f32_e32 v90, v149, v90
	v_add_f32_e32 v90, v150, v90
	v_add_f32_e32 v90, v151, v90
	v_cvt_pk_bf16_f32 v174, v146, v147
	v_cvt_pk_bf16_f32 v175, v148, v149
	v_mfma_f32_32x32x16_bf16 v[130:145], v[70:73], v[190:193], 0
	ds_read_b64_tr_b16 v[70:71], v241 offset:61440
	ds_read_b64_tr_b16 v[72:73], v241 offset:61952
	v_mfma_f32_32x32x16_bf16 v[98:113], v[86:89], v[190:193], 0
	v_add_f32_e32 v90, v152, v90
	v_add_f32_e32 v90, v153, v90
	v_add_f32_e32 v90, v154, v90
	v_add_f32_e32 v90, v155, v90
	v_cvt_pk_bf16_f32 v176, v150, v151
	v_cvt_pk_bf16_f32 v177, v152, v153
	ds_read_b64_tr_b16 v[86:87], v242 offset:40960
	ds_read_b64_tr_b16 v[88:89], v242 offset:41472
	v_add_f32_e32 v90, v156, v90
	v_add_f32_e32 v90, v157, v90
	v_add_f32_e32 v90, v158, v90
	v_add_f32_e32 v90, v159, v90
	v_cvt_pk_bf16_f32 v170, v154, v155
	v_cvt_pk_bf16_f32 v171, v156, v157
	v_mfma_f32_32x32x16_bf16 v[130:145], v[78:81], v[186:189], v[130:145]
	ds_read_b64_tr_b16 v[78:79], v242 offset:45056
	ds_read_b64_tr_b16 v[80:81], v242 offset:45568
	v_mfma_f32_32x32x16_bf16 v[98:113], v[94:97], v[186:189], v[98:113]
	v_add_f32_e32 v90, v160, v90
	v_add_f32_e32 v90, v161, v90
	v_add_f32_e32 v90, v114, v90
	v_add_f32_e32 v90, v115, v90
	v_cvt_pk_bf16_f32 v172, v158, v159
	v_cvt_pk_bf16_f32 v173, v160, v161
	s_nop 0
	v_add_f32_e32 v90, v116, v90
	v_add_f32_e32 v90, v117, v90
	v_add_f32_e32 v90, v118, v90
	v_add_f32_e32 v90, v119, v90
	v_cvt_pk_bf16_f32 v166, v114, v115
	v_cvt_pk_bf16_f32 v167, v116, v117
	v_mfma_f32_32x32x16_bf16 v[130:145], v[66:69], v[182:185], v[130:145]
	v_mfma_f32_32x32x16_bf16 v[98:113], v[196:199], v[182:185], v[98:113]
	v_add_f32_e32 v66, v120, v90
	v_add_f32_e32 v66, v121, v66
	v_add_f32_e32 v66, v122, v66
	v_add_f32_e32 v66, v123, v66
	v_cvt_pk_bf16_f32 v168, v118, v119
	v_cvt_pk_bf16_f32 v169, v120, v121
	s_nop 0
	v_add_f32_e32 v66, v124, v66
	v_add_f32_e32 v66, v125, v66
	v_add_f32_e32 v66, v126, v66
	v_add_f32_e32 v66, v127, v66
	v_cvt_pk_bf16_f32 v162, v122, v123
	v_cvt_pk_bf16_f32 v163, v124, v125
	s_waitcnt lgkmcnt(9)
; #define ATT_WAIT_BAR(N) asm volatile("s_waitcnt vmcnt(" #N ") lgkmcnt(0)\n\ts_barrier" ::: "memory")
; #define ROT() do { sl_prev = sl_cur; sl_cur = sl_next; sl_next = (sl_next == 2) ? 0 : sl_next + 1; } while (0)
; __device__ __forceinline__ void attn_unit(int b, int h, int qb, bool first, bool has_next, int nb, int nh, bf16_t* QO, const bf16_t* __restrict__ K, const bf16_t* __restrict__ V, float lam, char* shm) {
;     ...
;         STEP(pA0, pA1, pB0, pB1, NT - 2, false, true, true);   ATT_WAIT_BAR(0); ROT();
	v_mfma_f32_32x32x16_bf16 v[130:145], v[74:77], v[178:181], v[130:145]
	s_waitcnt lgkmcnt(8)
	v_mfma_f32_32x32x16_bf16 v[98:113], v[244:247], v[178:181], v[98:113]
	v_add_f32_e32 v66, v128, v66
	v_add_f32_e32 v66, v129, v66
	v_add_f32_e32 v114, 0, v66
	v_cvt_pk_bf16_f32 v164, v126, v127
	v_cvt_pk_bf16_f32 v165, v128, v129
	s_cmp_lg_u32 0, -1
	s_cselect_b32 s0, 0, 0
	s_add_i32 s0, s0, s90
	s_add_i32 s6, s0, 0xa000
	s_mov_b32 s7, m0
	s_mov_b32 m0, s6
	s_nop 0
	global_load_lds_dwordx4 v[218:219], off
	s_mov_b32 m0, s7
	s_add_i32 s0, s0, 0xc000
	s_mov_b32 s6, m0
	s_mov_b32 m0, s0
	s_nop 0
	global_load_lds_dwordx4 v[220:221], off
	s_mov_b32 m0, s6
	s_waitcnt lgkmcnt(6)
	v_mfma_f32_32x32x16_bf16 v[50:65], v[174:177], v[82:85], v[50:65]
	v_exp_f32_e32 v130, v130
	v_exp_f32_e32 v131, v131
	ds_read_b64_tr_b16 v[66:67], v241 offset:58368
	ds_read_b64_tr_b16 v[68:69], v241 offset:58880
	s_waitcnt lgkmcnt(6)
	v_mfma_f32_32x32x16_bf16 v[34:49], v[174:177], v[70:73], v[34:49]
	v_exp_f32_e32 v132, v132
	v_exp_f32_e32 v133, v133
	ds_read_b64_tr_b16 v[74:75], v241 offset:62464
	ds_read_b64_tr_b16 v[76:77], v241 offset:62976
	s_waitcnt lgkmcnt(6)
	v_mfma_f32_32x32x16_bf16 v[18:33], v[174:177], v[86:89], v[18:33]
	v_exp_f32_e32 v134, v134
	v_exp_f32_e32 v135, v135
	ds_read_b64_tr_b16 v[70:71], v242 offset:41984
	ds_read_b64_tr_b16 v[72:73], v242 offset:42496
	s_waitcnt lgkmcnt(6)
	v_mfma_f32_32x32x16_bf16 v[2:17], v[174:177], v[78:81], v[2:17]
	v_exp_f32_e32 v136, v136
	v_exp_f32_e32 v137, v137
	ds_read_b64_tr_b16 v[82:83], v242 offset:46080
	ds_read_b64_tr_b16 v[84:85], v242 offset:46592
	s_waitcnt lgkmcnt(6)
	v_mfma_f32_32x32x16_bf16 v[50:65], v[170:173], v[66:69], v[50:65]
	v_exp_f32_e32 v138, v138
	v_exp_f32_e32 v139, v139
	ds_read_b64_tr_b16 v[78:79], v241 offset:59392
	ds_read_b64_tr_b16 v[80:81], v241 offset:59904
	s_waitcnt lgkmcnt(6)
	v_mfma_f32_32x32x16_bf16 v[34:49], v[170:173], v[74:77], v[34:49]
	v_exp_f32_e32 v140, v140
	v_exp_f32_e32 v141, v141
	ds_read_b64_tr_b16 v[66:67], v241 offset:63488
	ds_read_b64_tr_b16 v[68:69], v241 offset:64000
	s_waitcnt lgkmcnt(6)
	v_mfma_f32_32x32x16_bf16 v[18:33], v[170:173], v[70:73], v[18:33]
	v_exp_f32_e32 v142, v142
	v_exp_f32_e32 v143, v143
	ds_read_b128 v[74:77], v243 offset:8192
	ds_read_b128 v[86:89], v243 offset:8704
	ds_read_b64_tr_b16 v[90:91], v242 offset:43008
	ds_read_b64_tr_b16 v[92:93], v242 offset:43520
	s_waitcnt lgkmcnt(8)
	v_mfma_f32_32x32x16_bf16 v[2:17], v[170:173], v[82:85], v[2:17]
	v_exp_f32_e32 v144, v144
	v_exp_f32_e32 v145, v145
	ds_read_b64_tr_b16 v[70:71], v242 offset:47104
	ds_read_b64_tr_b16 v[72:73], v242 offset:47616
	s_waitcnt lgkmcnt(8)
	v_mfma_f32_32x32x16_bf16 v[50:65], v[166:169], v[78:81], v[50:65]
	v_exp_f32_e32 v98, v98
	v_exp_f32_e32 v99, v99
	ds_read_b128 v[116:119], v243 offset:10240
	ds_read_b128 v[120:123], v243 offset:10752
	ds_read_b64_tr_b16 v[82:83], v241 offset:60416
	ds_read_b64_tr_b16 v[84:85], v241 offset:60928
	s_waitcnt lgkmcnt(10)
	v_mfma_f32_32x32x16_bf16 v[34:49], v[166:169], v[66:69], v[34:49]
	v_exp_f32_e32 v100, v100
	v_exp_f32_e32 v101, v101
	ds_read_b64_tr_b16 v[78:79], v241 offset:64512
	ds_read_b64_tr_b16 v[80:81], v241 offset:65024
	s_waitcnt lgkmcnt(8)
	v_mfma_f32_32x32x16_bf16 v[18:33], v[166:169], v[90:93], v[18:33]
	v_exp_f32_e32 v102, v102
	v_exp_f32_e32 v103, v103
	ds_read_b128 v[124:127], v243 offset:12288
	ds_read_b128 v[146:149], v243 offset:12800
	ds_read_b64_tr_b16 v[66:67], v242 offset:44032
	ds_read_b64_tr_b16 v[68:69], v242 offset:44544
	s_waitcnt lgkmcnt(10)
	v_mfma_f32_32x32x16_bf16 v[2:17], v[166:169], v[70:73], v[2:17]
	v_exp_f32_e32 v104, v104
	v_exp_f32_e32 v105, v105
	ds_read_b64_tr_b16 v[90:91], v242 offset:48128
	ds_read_b64_tr_b16 v[92:93], v242 offset:48640
	s_waitcnt lgkmcnt(8)
	v_mfma_f32_32x32x16_bf16 v[50:65], v[162:165], v[82:85], v[50:65]
	ds_read_b128 v[150:153], v243 offset:14336
	ds_read_b128 v[154:157], v243 offset:14848
	v_exp_f32_e32 v106, v106
	v_exp_f32_e32 v107, v107
	s_waitcnt lgkmcnt(8)
	v_mfma_f32_32x32x16_bf16 v[34:49], v[162:165], v[78:81], v[34:49]
	v_exp_f32_e32 v108, v108
	v_exp_f32_e32 v109, v109
	s_waitcnt lgkmcnt(4)
	v_mfma_f32_32x32x16_bf16 v[18:33], v[162:165], v[66:69], v[18:33]
	v_exp_f32_e32 v110, v110
	v_exp_f32_e32 v111, v111
	s_waitcnt lgkmcnt(2)
	v_mfma_f32_32x32x16_bf16 v[2:17], v[162:165], v[90:93], v[2:17]
	v_exp_f32_e32 v112, v112
	v_exp_f32_e32 v113, v113
	s_waitcnt vmcnt(0) lgkmcnt(0)
	s_barrier
; __device__ __forceinline__ void attn_unit(int b, int h, int qb, bool first, bool has_next, int nb, int nh, bf16_t* QO, const bf16_t* __restrict__ K, const bf16_t* __restrict__ V, float lam, char* shm) {
;     ...
;         STEP(pB0, pB1, pA0, pA1, NT - 1, false, false, false);
	ds_read_b64_tr_b16 v[158:159], v241 offset:24576
	ds_read_b64_tr_b16 v[160:161], v241 offset:25088
	v_add_f32_e32 v66, v130, v131
	v_add_f32_e32 v66, v132, v66
	v_add_f32_e32 v66, v133, v66
	v_add_f32_e32 v66, v134, v66
	v_add_f32_e32 v82, v135, v66
	v_mfma_f32_32x32x16_bf16 v[66:81], v[74:77], v[190:193], 0
	v_cvt_pk_bf16_f32 v174, v130, v131
	v_cvt_pk_bf16_f32 v175, v132, v133
	ds_read_b64_tr_b16 v[128:129], v241 offset:28672
	ds_read_b64_tr_b16 v[130:131], v241 offset:29184
	v_add_f32_e32 v82, v136, v82
	v_add_f32_e32 v82, v137, v82
	v_add_f32_e32 v82, v138, v82
	v_add_f32_e32 v115, v139, v82
	v_mfma_f32_32x32x16_bf16 v[82:97], v[86:89], v[190:193], 0
	v_cvt_pk_bf16_f32 v176, v134, v135
	v_cvt_pk_bf16_f32 v177, v136, v137
	ds_read_b64_tr_b16 v[132:133], v241 offset:32768
	ds_read_b64_tr_b16 v[134:135], v241 offset:33280
	v_mfma_f32_32x32x16_bf16 v[66:81], v[116:119], v[186:189], v[66:81]
	v_add_f32_e32 v115, v140, v115
	v_add_f32_e32 v115, v141, v115
	v_add_f32_e32 v115, v142, v115
	v_add_f32_e32 v115, v143, v115
	v_cvt_pk_bf16_f32 v170, v138, v139
	v_cvt_pk_bf16_f32 v171, v140, v141
	ds_read_b64_tr_b16 v[116:117], v241 offset:36864
	ds_read_b64_tr_b16 v[118:119], v241 offset:37376
	v_mfma_f32_32x32x16_bf16 v[82:97], v[120:123], v[186:189], v[82:97]
	v_add_f32_e32 v115, v144, v115
	v_add_f32_e32 v115, v145, v115
	v_add_f32_e32 v115, v98, v115
	v_add_f32_e32 v115, v99, v115
	v_cvt_pk_bf16_f32 v172, v142, v143
	v_cvt_pk_bf16_f32 v173, v144, v145
	v_mfma_f32_32x32x16_bf16 v[66:81], v[124:127], v[182:185], v[66:81]
	v_add_f32_e32 v115, v100, v115
	v_add_f32_e32 v115, v101, v115
	v_add_f32_e32 v115, v102, v115
	v_add_f32_e32 v115, v103, v115
	v_cvt_pk_bf16_f32 v166, v98, v99
	v_cvt_pk_bf16_f32 v167, v100, v101
	v_mfma_f32_32x32x16_bf16 v[82:97], v[146:149], v[182:185], v[82:97]
	v_add_f32_e32 v98, v104, v115
	v_add_f32_e32 v98, v105, v98
	v_add_f32_e32 v98, v106, v98
	v_add_f32_e32 v98, v107, v98
	v_cvt_pk_bf16_f32 v168, v102, v103
	v_cvt_pk_bf16_f32 v169, v104, v105
	s_waitcnt lgkmcnt(9)
	v_mfma_f32_32x32x16_bf16 v[66:81], v[150:153], v[178:181], v[66:81]
	v_add_f32_e32 v98, v108, v98
	v_add_f32_e32 v98, v109, v98
	v_add_f32_e32 v98, v110, v98
	v_add_f32_e32 v98, v111, v98
	v_cvt_pk_bf16_f32 v162, v106, v107
	v_cvt_pk_bf16_f32 v163, v108, v109
	s_waitcnt lgkmcnt(8)
	v_mfma_f32_32x32x16_bf16 v[82:97], v[154:157], v[178:181], v[82:97]
	v_add_f32_e32 v98, v112, v98
	v_add_f32_e32 v98, v113, v98
	v_add_f32_e32 v98, 0, v98
	v_cvt_pk_bf16_f32 v164, v110, v111
	v_cvt_pk_bf16_f32 v165, v112, v113
	s_waitcnt lgkmcnt(6)
	v_mfma_f32_32x32x16_bf16 v[50:65], v[174:177], v[158:161], v[50:65]
	v_exp_f32_e32 v66, v66
	v_exp_f32_e32 v67, v67
	ds_read_b64_tr_b16 v[100:101], v241 offset:25600
	ds_read_b64_tr_b16 v[102:103], v241 offset:26112
	s_waitcnt lgkmcnt(6)
	v_mfma_f32_32x32x16_bf16 v[34:49], v[174:177], v[128:131], v[34:49]
	v_exp_f32_e32 v68, v68
	v_exp_f32_e32 v69, v69
	ds_read_b64_tr_b16 v[104:105], v241 offset:29696
	ds_read_b64_tr_b16 v[106:107], v241 offset:30208
	s_waitcnt lgkmcnt(6)
	v_mfma_f32_32x32x16_bf16 v[18:33], v[174:177], v[132:135], v[18:33]
	v_exp_f32_e32 v70, v70
	v_exp_f32_e32 v71, v71
	ds_read_b64_tr_b16 v[108:109], v241 offset:33792
	ds_read_b64_tr_b16 v[110:111], v241 offset:34304
	s_waitcnt lgkmcnt(6)
	v_mfma_f32_32x32x16_bf16 v[2:17], v[174:177], v[116:119], v[2:17]
	v_exp_f32_e32 v72, v72
	v_exp_f32_e32 v73, v73
	ds_read_b64_tr_b16 v[120:121], v241 offset:37888
	ds_read_b64_tr_b16 v[122:123], v241 offset:38400
	s_waitcnt lgkmcnt(6)
	v_mfma_f32_32x32x16_bf16 v[50:65], v[170:173], v[100:103], v[50:65]
	v_exp_f32_e32 v74, v74
	v_exp_f32_e32 v75, v75
	ds_read_b64_tr_b16 v[116:117], v241 offset:26624
	ds_read_b64_tr_b16 v[118:119], v241 offset:27136
	s_waitcnt lgkmcnt(6)
	v_mfma_f32_32x32x16_bf16 v[34:49], v[170:173], v[104:107], v[34:49]
	v_exp_f32_e32 v76, v76
	v_exp_f32_e32 v77, v77
	ds_read_b64_tr_b16 v[100:101], v241 offset:30720
	ds_read_b64_tr_b16 v[102:103], v241 offset:31232
	s_waitcnt lgkmcnt(6)
	v_mfma_f32_32x32x16_bf16 v[18:33], v[170:173], v[108:111], v[18:33]
	v_exp_f32_e32 v78, v78
	v_exp_f32_e32 v79, v79
	ds_read_b64_tr_b16 v[104:105], v241 offset:34816
	ds_read_b64_tr_b16 v[106:107], v241 offset:35328
	s_waitcnt lgkmcnt(6)
	v_mfma_f32_32x32x16_bf16 v[2:17], v[170:173], v[120:123], v[2:17]
	v_exp_f32_e32 v80, v80
	v_exp_f32_e32 v81, v81
	ds_read_b64_tr_b16 v[108:109], v241 offset:38912
	ds_read_b64_tr_b16 v[110:111], v241 offset:39424
	s_waitcnt lgkmcnt(6)
	v_mfma_f32_32x32x16_bf16 v[50:65], v[166:169], v[116:119], v[50:65]
	v_exp_f32_e32 v82, v82
	v_exp_f32_e32 v83, v83
	ds_read_b64_tr_b16 v[120:121], v241 offset:27648
	ds_read_b64_tr_b16 v[122:123], v241 offset:28160
	s_waitcnt lgkmcnt(6)
	v_mfma_f32_32x32x16_bf16 v[34:49], v[166:169], v[100:103], v[34:49]
	v_exp_f32_e32 v84, v84
	v_exp_f32_e32 v85, v85
	ds_read_b64_tr_b16 v[116:117], v241 offset:31744
	ds_read_b64_tr_b16 v[118:119], v241 offset:32256
	s_waitcnt lgkmcnt(6)
	v_mfma_f32_32x32x16_bf16 v[18:33], v[166:169], v[104:107], v[18:33]
	v_exp_f32_e32 v86, v86
	v_exp_f32_e32 v87, v87
	ds_read_b64_tr_b16 v[100:101], v241 offset:35840
	ds_read_b64_tr_b16 v[102:103], v241 offset:36352
	s_waitcnt lgkmcnt(6)
	v_mfma_f32_32x32x16_bf16 v[2:17], v[166:169], v[108:111], v[2:17]
	v_exp_f32_e32 v88, v88
	v_exp_f32_e32 v89, v89
	ds_read_b64_tr_b16 v[104:105], v241 offset:39936
	ds_read_b64_tr_b16 v[106:107], v241 offset:40448
	s_waitcnt lgkmcnt(6)
; __device__ __forceinline__ s16x4 vtr(lds_cptr p) { return __builtin_bit_cast(s16x4, __builtin_amdgcn_ds_read_tr16_b64_v4i16((LAS v4i16_t*)p)); }
; __device__ __forceinline__ void attn_unit(int b, int h, int qb, bool first, bool has_next, int nb, int nh, bf16_t* QO, const bf16_t* __restrict__ K, const bf16_t* __restrict__ V, float lam, char* shm) {
;     ...
;         { float sacc = pB0[0] + pB0[1];
; #pragma unroll
;           for (int r = 2; r < 16; ++r) sacc += pB0[r];
; #pragma unroll
;           for (int r = 0; r < 16; ++r) sacc += pB1[r];
;           l_reg += sacc;
;           pw0 = (u32x4){ATT_PK(pB0[0], pB0[1]), ATT_PK(pB0[2], pB0[3]), ATT_PK(pB0[4], pB0[5]), ATT_PK(pB0[6], pB0[7])};
;           pw1 = (u32x4){ATT_PK(pB0[8], pB0[9]), ATT_PK(pB0[10], pB0[11]), ATT_PK(pB0[12], pB0[13]), ATT_PK(pB0[14], pB0[15])};
;           pw2 = (u32x4){ATT_PK(pB1[0], pB1[1]), ATT_PK(pB1[2], pB1[3]), ATT_PK(pB1[4], pB1[5]), ATT_PK(pB1[6], pB1[7])};
;           pw3 = (u32x4){ATT_PK(pB1[8], pB1[9]), ATT_PK(pB1[10], pB1[11]), ATT_PK(pB1[12], pB1[13]), ATT_PK(pB1[14], pB1[15])};
;           ATT_SB();
;           const lds_cptr vp = vp0 + sl_cur * VSLOT;
; #pragma unroll
;           for (int d0 = 0; d0 < 4; ++d0) {
;               const s16x4 l0 = vtr(vp + d0 * 4096), h0 = vtr(vp + d0 * 4096 + 512), l1 = vtr(vp + d0 * 4096 + 1024), h1 = vtr(vp + d0 * 4096 + 1536);
;               const s16x4 l2 = vtr(vp + d0 * 4096 + 2048), h2 = vtr(vp + d0 * 4096 + 2560), l3 = vtr(vp + d0 * 4096 + 3072), h3 = vtr(vp + d0 * 4096 + 3584);
;               o[d0] = ATT_MFMA(PAF(0), ((bf16x8){l0[0], l0[1], l0[2], l0[3], h0[0], h0[1], h0[2], h0[3]}), o[d0]);
;               o[d0] = ATT_MFMA(PAF(1), ((bf16x8){l1[0], l1[1], l1[2], l1[3], h1[0], h1[1], h1[2], h1[3]}), o[d0]);
;               o[d0] = ATT_MFMA(PAF(2), ((bf16x8){l2[0], l2[1], l2[2], l2[3], h2[0], h2[1], h2[2], h2[3]}), o[d0]);
;               o[d0] = ATT_MFMA(PAF(3), ((bf16x8){l3[0], l3[1], l3[2], l3[3], h3[0], h3[1], h3[2], h3[3]}), o[d0]); } }
;     ...
;         ATT_SB();
;         asm volatile("s_waitcnt lgkmcnt(0)\n\ts_barrier" ::: "memory");
;         ATT_SB();
;         if (map == 0 || has_next) {
;             const bf16_t* nk = (map == 0) ? ksrc + 1024 : K + (long)nb * SEQ * DM + (2 * nh) * 1024 + klane;
;             const bf16_t* nv = (map == 0) ? vsrc0 : V + (long)nb * SEQ * DM + nh * 2048 + vlane;
	v_mfma_f32_32x32x16_bf16 v[50:65], v[162:165], v[120:123], v[50:65]
	v_exp_f32_e32 v90, v90
	v_exp_f32_e32 v91, v91
	s_waitcnt lgkmcnt(4)
	v_mfma_f32_32x32x16_bf16 v[34:49], v[162:165], v[116:119], v[34:49]
	v_exp_f32_e32 v92, v92
	v_exp_f32_e32 v93, v93
	s_waitcnt lgkmcnt(2)
	v_mfma_f32_32x32x16_bf16 v[18:33], v[162:165], v[100:103], v[18:33]
	v_exp_f32_e32 v94, v94
	v_exp_f32_e32 v95, v95
	s_waitcnt lgkmcnt(0)
	v_mfma_f32_32x32x16_bf16 v[2:17], v[162:165], v[104:107], v[2:17]
	v_exp_f32_e32 v96, v96
	v_exp_f32_e32 v97, v97
	v_cvt_pk_bf16_f32 v176, v70, v71
	v_cvt_pk_bf16_f32 v177, v72, v73
	v_cvt_pk_bf16_f32 v172, v78, v79
	v_cvt_pk_bf16_f32 v173, v80, v81
	v_cvt_pk_bf16_f32 v168, v86, v87
	v_cvt_pk_bf16_f32 v169, v88, v89
	v_cvt_pk_bf16_f32 v164, v94, v95
	v_cvt_pk_bf16_f32 v165, v96, v97
	v_cvt_pk_bf16_f32 v174, v66, v67
	v_cvt_pk_bf16_f32 v175, v68, v69
	v_cvt_pk_bf16_f32 v170, v74, v75
	v_cvt_pk_bf16_f32 v171, v76, v77
	v_cvt_pk_bf16_f32 v166, v82, v83
	v_cvt_pk_bf16_f32 v167, v84, v85
	v_cvt_pk_bf16_f32 v162, v90, v91
	v_cvt_pk_bf16_f32 v163, v92, v93
	ds_read_b64_tr_b16 v[100:101], v241 offset:40960
	ds_read_b64_tr_b16 v[102:103], v241 offset:41472
	ds_read_b64_tr_b16 v[104:105], v241 offset:41984
	ds_read_b64_tr_b16 v[106:107], v241 offset:42496
	s_waitcnt lgkmcnt(2)
	v_mfma_f32_32x32x16_bf16 v[50:65], v[174:177], v[100:103], v[50:65]
	s_waitcnt lgkmcnt(0)
	v_mfma_f32_32x32x16_bf16 v[50:65], v[170:173], v[104:107], v[50:65]
	ds_read_b64_tr_b16 v[100:101], v241 offset:43008
	ds_read_b64_tr_b16 v[102:103], v241 offset:43520
	ds_read_b64_tr_b16 v[104:105], v241 offset:44032
	ds_read_b64_tr_b16 v[106:107], v241 offset:44544
	s_waitcnt lgkmcnt(2)
	v_mfma_f32_32x32x16_bf16 v[50:65], v[166:169], v[100:103], v[50:65]
	s_waitcnt lgkmcnt(0)
	v_mfma_f32_32x32x16_bf16 v[50:65], v[162:165], v[104:107], v[50:65]
	ds_read_b64_tr_b16 v[100:101], v241 offset:45056
	ds_read_b64_tr_b16 v[102:103], v241 offset:45568
	ds_read_b64_tr_b16 v[104:105], v241 offset:46080
	ds_read_b64_tr_b16 v[106:107], v241 offset:46592
	s_waitcnt lgkmcnt(2)
	v_mfma_f32_32x32x16_bf16 v[34:49], v[174:177], v[100:103], v[34:49]
	s_waitcnt lgkmcnt(0)
	v_mfma_f32_32x32x16_bf16 v[34:49], v[170:173], v[104:107], v[34:49]
	ds_read_b64_tr_b16 v[100:101], v241 offset:47104
	ds_read_b64_tr_b16 v[102:103], v241 offset:47616
	ds_read_b64_tr_b16 v[104:105], v241 offset:48128
	ds_read_b64_tr_b16 v[106:107], v241 offset:48640
	s_waitcnt lgkmcnt(2)
	v_mfma_f32_32x32x16_bf16 v[34:49], v[166:169], v[100:103], v[34:49]
	s_waitcnt lgkmcnt(0)
	v_mfma_f32_32x32x16_bf16 v[34:49], v[162:165], v[104:107], v[34:49]
	ds_read_b64_tr_b16 v[100:101], v241 offset:49152
	ds_read_b64_tr_b16 v[102:103], v241 offset:49664
	ds_read_b64_tr_b16 v[104:105], v241 offset:50176
	ds_read_b64_tr_b16 v[106:107], v241 offset:50688
	s_waitcnt lgkmcnt(2)
	v_mfma_f32_32x32x16_bf16 v[18:33], v[174:177], v[100:103], v[18:33]
	s_waitcnt lgkmcnt(0)
	v_mfma_f32_32x32x16_bf16 v[18:33], v[170:173], v[104:107], v[18:33]
	ds_read_b64_tr_b16 v[100:101], v241 offset:51200
	ds_read_b64_tr_b16 v[102:103], v241 offset:51712
	ds_read_b64_tr_b16 v[104:105], v241 offset:52224
	ds_read_b64_tr_b16 v[106:107], v241 offset:52736
	s_waitcnt lgkmcnt(2)
	v_mfma_f32_32x32x16_bf16 v[18:33], v[166:169], v[100:103], v[18:33]
	s_waitcnt lgkmcnt(0)
	v_mfma_f32_32x32x16_bf16 v[18:33], v[162:165], v[104:107], v[18:33]
	ds_read_b64_tr_b16 v[100:101], v241 offset:53248
	ds_read_b64_tr_b16 v[102:103], v241 offset:53760
	ds_read_b64_tr_b16 v[104:105], v241 offset:54272
	ds_read_b64_tr_b16 v[106:107], v241 offset:54784
	s_waitcnt lgkmcnt(2)
	v_mfma_f32_32x32x16_bf16 v[2:17], v[174:177], v[100:103], v[2:17]
	s_waitcnt lgkmcnt(0)
	v_mfma_f32_32x32x16_bf16 v[2:17], v[170:173], v[104:107], v[2:17]
	ds_read_b64_tr_b16 v[100:101], v241 offset:55296
	ds_read_b64_tr_b16 v[102:103], v241 offset:55808
	ds_read_b64_tr_b16 v[104:105], v241 offset:56320
	ds_read_b64_tr_b16 v[106:107], v241 offset:56832
	s_waitcnt lgkmcnt(2)
	v_mfma_f32_32x32x16_bf16 v[2:17], v[166:169], v[100:103], v[2:17]
	s_waitcnt lgkmcnt(0)
	v_mfma_f32_32x32x16_bf16 v[2:17], v[162:165], v[104:107], v[2:17]
	s_waitcnt lgkmcnt(0)
	s_barrier
	s_or_b64 s[6:7], s[48:49], s[54:55]
	s_andn2_b64 vcc, exec, s[6:7]
	s_cbranch_vccnz .LBB0_378
	v_lshl_add_u64 v[100:101], v[232:233], 0, s[2:3]
	v_cndmask_b32_e64 v101, v223, v101, s[54:55]
	v_cndmask_b32_e64 v100, v222, v100, s[54:55]
	s_mov_b32 s0, m0
	s_mov_b32 m0, s91
	s_nop 0
	global_load_lds_dwordx4 v[100:101], off
	s_mov_b32 m0, s0
	v_cndmask_b32_e64 v103, v225, v205, s[54:55]
	v_cndmask_b32_e64 v102, v224, v204, s[54:55]
	s_mov_b32 s0, m0
	s_mov_b32 m0, s92
	s_nop 0
	global_load_lds_dwordx4 v[102:103], off
	s_mov_b32 m0, s0
	s_cmp_lg_u32 0, -1
	s_cselect_b32 s0, 0, 0
	s_add_i32 s0, s0, s90
	v_lshl_add_u64 v[102:103], v[102:103], 0, s[2:3]
	s_add_i32 s6, s0, 0x8000
	s_mov_b32 s7, m0
	s_mov_b32 m0, s6
	s_nop 0
	global_load_lds_dwordx4 v[102:103], off
	s_mov_b32 m0, s7
	v_lshl_add_u64 v[102:103], v[100:101], 0, s[4:5]
	s_add_i32 s6, s0, 0x2000
	s_mov_b32 s7, m0
	s_mov_b32 m0, s6
	s_nop 0
	global_load_lds_dwordx4 v[102:103], off
	s_mov_b32 m0, s7
	v_lshl_add_u64 v[100:101], v[100:101], 0, s[22:23]
	s_addk_i32 s0, 0x4000
	s_mov_b32 s6, m0
	s_mov_b32 m0, s0
	s_nop 0
	global_load_lds_dwordx4 v[100:101], off
	s_mov_b32 m0, s6

; __device__ __forceinline__ unsigned xb_ld(unsigned* p)              { return __hip_atomic_load(p, __ATOMIC_RELAXED, __HIP_MEMORY_SCOPE_AGENT); }
; #define XB_SPIN(cond, bar) do { unsigned _sp = 0; while (cond) { __builtin_amdgcn_s_sleep(1); \
;     if ((++_sp & 255u) == 0u) { if (xb_ld(&(bar)[XB_TMO])) break; if (_sp > XB_SPIN_CAP) { atomicAdd(&(bar)[XB_TMO], 1u); break; } } } } while (0)
; __device__ __forceinline__ void xcd_split_wait(unsigned* w, const XcdBarrier& b) {
;     if (threadIdx.x == 0) {
;         XB_SPIN(xb_ld(&w[XB_TOPGEN]) == 0u, b.bar);
;         __builtin_amdgcn_fence(__ATOMIC_ACQUIRE, "agent");
;         asm volatile("s_waitcnt vmcnt(0)" ::: "memory");
;     }
;     __syncthreads();
; __global__ void __launch_bounds__(512, 2) fwd_kernel(Args args) {
;     ...
;         for (int i = 0; ; ++i) { const int L = i * G + vcu, NU = NBATCH * NH * (SEQ / 256); if (L >= NU) break;
;             const int bh = L >> 3, qb = L & 7, Ln = L + G, nbh = Ln >> 3;
;             att::attn_unit(bh >> 3, bh & 7, qb, i == 0, Ln < NU, nbh >> 3, nbh & 7, QO, KB, VB, lam, (char*)lds_raw); }
;         __syncthreads();
;         xcd_split_wait(BARW + 8192, xbar);
.LBB0_385:
	s_setprio 0
	s_waitcnt lgkmcnt(0)
	s_barrier
	s_mov_b64 s[0:1], exec
	v_readlane_b32 s2, v248, 2
	v_readlane_b32 s3, v248, 3
	s_and_b64 s[2:3], s[0:1], s[2:3]
	s_mov_b64 exec, s[2:3]
	s_cbranch_execz .LBB0_400
	v_mov_b32_e32 v1, 0xb000
	global_load_dword v1, v1, s[62:63] offset:1280 sc1
	s_add_u32 s2, s62, 0xb500
	s_addc_u32 s3, s63, 0
	s_waitcnt vmcnt(0)
	v_cmp_ne_u32_e32 vcc, 0, v1
	s_cbranch_vccnz .LBB0_399
	s_mov_b32 s6, 1
	v_mov_b32_e32 v1, 0
	s_branch .LBB0_389
